# pipelined norm row loops (next-row prefetch, batched param loads) in phases 6,10,17
# speedup vs baseline: 1.0610x; 1.0043x over previous
.LBB0_1397:
	s_cmp_gt_i32 s44, 6
	s_waitcnt lgkmcnt(0)
	s_cselect_b64 s[2:3], -1, 0
	s_cmp_lt_i32 s45, 7
	s_cselect_b64 s[4:5], -1, 0
	s_or_b64 s[2:3], s[2:3], s[4:5]
	s_and_b64 vcc, exec, s[2:3]
	s_cbranch_vccnz .LBB0_1457
	v_mbcnt_hi_u32_b32 v38, -1, v210
	v_mov_b32_e32 v0, v38
	v_mov_b32_e32 v1, v38
	s_mov_b32 s2, 0x8000
	v_add_u32_e32 v1, s70, v1
	v_ashrrev_i32_e32 v1, 6, v1
	v_lshl_add_u32 v16, s22, 3, v1
	v_cmp_gt_i32_e32 vcc, s2, v16
	s_and_saveexec_b64 s[4:5], vcc
	s_cbranch_execz .LBB0_1403
	s_load_dwordx2 s[6:7], s[0:1], 0x140
	s_load_dwordx2 s[10:11], s[0:1], 0x158
	s_load_dwordx2 s[2:3], s[0:1], 0x18
	s_load_dwordx2 s[14:15], s[0:1], 0xb8
	v_and_b32_e32 v1, 63, v0
	v_and_b32_e32 v0, 64, v38
	v_add_u32_e32 v2, 64, v0
	s_waitcnt lgkmcnt(0)
	s_add_u32 s16, s2, 0x1000
	v_xor_b32_e32 v3, 32, v38
	s_addc_u32 s17, s3, 0
	v_cmp_lt_i32_e64 s[2:3], v3, v2
	v_lshlrev_b32_e32 v0, 2, v1
	v_mov_b32_e32 v19, 0
	v_cndmask_b32_e64 v3, v38, v3, s[2:3]
	v_lshlrev_b32_e32 v39, 2, v3
	v_xor_b32_e32 v3, 16, v38
	v_cmp_lt_i32_e64 s[2:3], v3, v2
	v_mov_b32_e32 v5, v19
	v_mov_b32_e32 v7, v19
	v_cndmask_b32_e64 v3, v38, v3, s[2:3]
	v_lshlrev_b32_e32 v40, 2, v3
	v_xor_b32_e32 v3, 8, v38
	v_cmp_lt_i32_e64 s[2:3], v3, v2
	v_lshlrev_b32_e32 v18, 4, v1
	v_lshl_add_u64 v[20:21], s[16:17], 0, v[18:19]
	v_cndmask_b32_e64 v3, v38, v3, s[2:3]
	v_lshlrev_b32_e32 v41, 2, v3
	v_xor_b32_e32 v3, 4, v38
	v_cmp_lt_i32_e64 s[2:3], v3, v2
	v_mov_b32_e32 v9, v19
	v_lshl_add_u64 v[28:29], s[14:15], 0, v[18:19]
	v_cndmask_b32_e64 v3, v38, v3, s[2:3]
	v_lshlrev_b32_e32 v42, 2, v3
	v_xor_b32_e32 v3, 2, v38
	v_cmp_lt_i32_e64 s[2:3], v3, v2
	v_lshlrev_b32_e32 v18, 3, v1
	s_mov_b64 s[8:9], 0x1000
	v_cndmask_b32_e64 v3, v38, v3, s[2:3]
	v_lshlrev_b32_e32 v43, 2, v3
	v_xor_b32_e32 v3, 1, v38
	v_cmp_lt_i32_e64 s[2:3], v3, v2
	v_cmp_eq_u32_e32 vcc, 0, v1
	s_lshl_b32 s12, s42, 3
	v_cndmask_b32_e64 v2, v38, v3, s[2:3]
	v_lshlrev_b32_e32 v44, 2, v2
	v_or_b32_e32 v2, 0x100, v0
	v_lshlrev_b32_e32 v4, 2, v2
	v_lshl_add_u64 v[22:23], s[16:17], 0, v[4:5]
	v_or_b32_e32 v4, 0x200, v0
	v_lshlrev_b32_e32 v6, 2, v4
	v_lshl_add_u64 v[24:25], s[16:17], 0, v[6:7]
	v_or_b32_e32 v6, 0x300, v0
	v_lshlrev_b32_e32 v8, 2, v6
	v_lshl_add_u64 v[26:27], s[16:17], 0, v[8:9]
	v_lshl_add_u64 v[30:31], s[10:11], 0, v[18:19]
	s_mov_b64 s[10:11], 0
	v_mov_b32_e32 v45, 0x358637bd
	s_mov_b32 s13, 0x800000
	v_lshlrev_b32_e32 v18, 2, v0
	v_lshlrev_b32_e32 v32, 2, v2
	v_mov_b32_e32 v33, v19
	v_lshlrev_b32_e32 v34, 2, v4
	v_mov_b32_e32 v35, v19
	v_lshlrev_b32_e32 v36, 2, v6
	v_mov_b32_e32 v37, v19
	s_movk_i32 s14, 0x7fff
	v_ashrrev_i32_e32 v17, 31, v16
	v_lshlrev_b64 v[134:135], 12, v[16:17]
	v_lshl_add_u64 v[134:135], v[28:29], 0, v[134:135]
	global_load_dwordx4 v[118:121], v[134:135], off
	global_load_dwordx4 v[122:125], v[134:135], off offset:1024
	global_load_dwordx4 v[126:129], v[134:135], off offset:2048
	global_load_dwordx4 v[130:133], v[134:135], off offset:3072
	s_waitcnt vmcnt(0)
	s_branch .LBB0_1401
.LBB0_1400:
	s_or_b64 exec, exec, s[2:3]
	s_waitcnt lgkmcnt(0)
	v_add_f32_e32 v46, v46, v47
	v_fmamk_f32 v46, v46, 0x3a800000, v45
	v_mul_f32_e32 v47, 0x4b800000, v46
	v_cmp_gt_f32_e64 s[2:3], s13, v46
	s_nop 1
	v_cndmask_b32_e64 v46, v46, v47, s[2:3]
	v_rsq_f32_e32 v68, v46
	v_lshlrev_b64 v[46:47], 10, v[16:17]
	v_lshl_add_u64 v[64:65], v[46:47], 1, v[30:31]
	v_add_u32_e32 v16, s12, v16
	v_mul_f32_e32 v17, 0x45800000, v68
	v_cndmask_b32_e64 v68, v68, v17, s[2:3]
	v_pk_mul_f32 v[12:13], v[12:13], v[68:69] op_sel_hi:[1,0]
	v_pk_mul_f32 v[14:15], v[14:15], v[68:69] op_sel_hi:[1,0]
	v_pk_mul_f32 v[8:9], v[8:9], v[68:69] op_sel_hi:[1,0]
	v_pk_mul_f32 v[10:11], v[10:11], v[68:69] op_sel_hi:[1,0]
	v_pk_mul_f32 v[4:5], v[4:5], v[68:69] op_sel_hi:[1,0]
	v_pk_mul_f32 v[6:7], v[6:7], v[68:69] op_sel_hi:[1,0]
	v_pk_mul_f32 v[0:1], v[0:1], v[68:69] op_sel_hi:[1,0]
	v_pk_mul_f32 v[2:3], v[2:3], v[68:69] op_sel_hi:[1,0]
	v_cmp_lt_i32_e64 s[2:3], s14, v16
	s_or_b64 s[10:11], s[2:3], s[10:11]
	s_waitcnt vmcnt(6)
	v_pk_mul_f32 v[12:13], v[12:13], v[70:71]
	v_pk_mul_f32 v[14:15], v[14:15], v[72:73]
	v_pk_add_f32 v[86:87], v[86:87], 1.0 op_sel_hi:[1,0]
	v_pk_add_f32 v[88:89], v[88:89], 1.0 op_sel_hi:[1,0]
	v_pk_fma_f32 v[12:13], v[12:13], v[86:87], v[102:103]
	v_pk_fma_f32 v[14:15], v[14:15], v[88:89], v[104:105]
	v_cvt_pk_bf16_f32 v12, v12, v13
	v_cvt_pk_bf16_f32 v13, v14, v15
	global_store_dwordx2 v[64:65], v[12:13], off
	v_pk_mul_f32 v[8:9], v[8:9], v[74:75]
	v_pk_mul_f32 v[10:11], v[10:11], v[76:77]
	v_pk_add_f32 v[90:91], v[90:91], 1.0 op_sel_hi:[1,0]
	v_pk_add_f32 v[92:93], v[92:93], 1.0 op_sel_hi:[1,0]
	v_pk_fma_f32 v[8:9], v[8:9], v[90:91], v[106:107]
	v_pk_fma_f32 v[10:11], v[10:11], v[92:93], v[108:109]
	v_cvt_pk_bf16_f32 v8, v8, v9
	v_cvt_pk_bf16_f32 v9, v10, v11
	global_store_dwordx2 v[64:65], v[8:9], off offset:512
	v_pk_mul_f32 v[4:5], v[4:5], v[78:79]
	v_pk_mul_f32 v[6:7], v[6:7], v[80:81]
	v_pk_add_f32 v[94:95], v[94:95], 1.0 op_sel_hi:[1,0]
	v_pk_add_f32 v[96:97], v[96:97], 1.0 op_sel_hi:[1,0]
	v_pk_fma_f32 v[4:5], v[4:5], v[94:95], v[110:111]
	v_pk_fma_f32 v[6:7], v[6:7], v[96:97], v[112:113]
	v_cvt_pk_bf16_f32 v4, v4, v5
	v_cvt_pk_bf16_f32 v5, v6, v7
	global_store_dwordx2 v[64:65], v[4:5], off offset:1024
	v_pk_mul_f32 v[0:1], v[0:1], v[82:83]
	v_pk_mul_f32 v[2:3], v[2:3], v[84:85]
	v_pk_add_f32 v[98:99], v[98:99], 1.0 op_sel_hi:[1,0]
	v_pk_add_f32 v[100:101], v[100:101], 1.0 op_sel_hi:[1,0]
	v_pk_fma_f32 v[0:1], v[0:1], v[98:99], v[114:115]
	v_pk_fma_f32 v[2:3], v[2:3], v[100:101], v[116:117]
	v_cvt_pk_bf16_f32 v0, v0, v1
	v_cvt_pk_bf16_f32 v1, v2, v3
	global_store_dwordx2 v[64:65], v[0:1], off offset:1536
	s_waitcnt vmcnt(6)
	s_andn2_b64 exec, exec, s[10:11]
	s_cbranch_execz .LBB0_1403
.LBB0_1401:
	v_mov_b32_e32 v12, v118
	v_mov_b32_e32 v13, v119
	v_mov_b32_e32 v14, v120
	v_mov_b32_e32 v15, v121
	v_mov_b32_e32 v8, v122
	v_mov_b32_e32 v9, v123
	v_mov_b32_e32 v10, v124
	v_mov_b32_e32 v11, v125
	v_mov_b32_e32 v4, v126
	v_mov_b32_e32 v5, v127
	v_mov_b32_e32 v6, v128
	v_mov_b32_e32 v7, v129
	v_mov_b32_e32 v0, v130
	v_mov_b32_e32 v1, v131
	v_mov_b32_e32 v2, v132
	v_mov_b32_e32 v3, v133
	v_ashrrev_i32_e32 v17, 31, v16
	v_ashrrev_i32_e32 v134, 12, v16
	v_add_u32_e32 v134, 8, v134
	v_mul_hi_i32_i24_e32 v135, 0x3000, v134
	v_mul_i32_i24_e32 v134, 0x3000, v134
	v_lshl_add_u64 v[136:137], s[6:7], 0, v[134:135]
	v_lshl_add_u64 v[138:139], v[136:137], 0, s[8:9]
	global_load_dwordx4 v[70:73], v[20:21], off
	global_load_dwordx4 v[74:77], v[22:23], off
	global_load_dwordx4 v[78:81], v[24:25], off
	global_load_dwordx4 v[82:85], v[26:27], off
	v_lshl_add_u64 v[140:141], v[138:139], 0, v[18:19]
	global_load_dwordx4 v[86:89], v[140:141], off
	v_lshl_add_u64 v[140:141], v[138:139], 0, v[32:33]
	global_load_dwordx4 v[90:93], v[140:141], off
	v_lshl_add_u64 v[140:141], v[138:139], 0, v[34:35]
	global_load_dwordx4 v[94:97], v[140:141], off
	v_lshl_add_u64 v[140:141], v[138:139], 0, v[36:37]
	global_load_dwordx4 v[98:101], v[140:141], off
	v_lshl_add_u64 v[142:143], v[136:137], 0, v[18:19]
	global_load_dwordx4 v[102:105], v[142:143], off
	global_load_dwordx4 v[106:109], v[142:143], off offset:1024
	global_load_dwordx4 v[110:113], v[142:143], off offset:2048
	global_load_dwordx4 v[114:117], v[142:143], off offset:3072
	v_add_u32_e32 v144, s12, v16
	v_min_i32_e32 v144, 0x7fff, v144
	v_ashrrev_i32_e32 v145, 31, v144
	v_lshlrev_b64 v[146:147], 12, v[144:145]
	v_lshl_add_u64 v[146:147], v[28:29], 0, v[146:147]
	global_load_dwordx4 v[118:121], v[146:147], off
	global_load_dwordx4 v[122:125], v[146:147], off offset:1024
	global_load_dwordx4 v[126:129], v[146:147], off offset:2048
	global_load_dwordx4 v[130:133], v[146:147], off offset:3072
	v_mov_b32_e32 v48, v13
	v_mov_b32_e32 v49, v9
	v_mov_b32_e32 v46, v12
	v_mov_b32_e32 v47, v8
	v_mov_b32_e32 v56, v5
	v_mov_b32_e32 v57, v1
	v_pk_mul_f32 v[48:49], v[48:49], v[48:49]
	v_mov_b32_e32 v50, v14
	v_mov_b32_e32 v51, v10
	v_mov_b32_e32 v54, v4
	v_mov_b32_e32 v55, v0
	v_pk_mul_f32 v[56:57], v[56:57], v[56:57]
	v_pk_fma_f32 v[46:47], v[46:47], v[46:47], v[48:49]
	v_mov_b32_e32 v52, v15
	v_mov_b32_e32 v53, v11
	v_mov_b32_e32 v58, v6
	v_mov_b32_e32 v59, v2
	v_pk_fma_f32 v[48:49], v[54:55], v[54:55], v[56:57]
	v_pk_fma_f32 v[46:47], v[50:51], v[50:51], v[46:47]
	v_mov_b32_e32 v60, v7
	v_mov_b32_e32 v61, v3
	v_pk_fma_f32 v[48:49], v[58:59], v[58:59], v[48:49]
	v_pk_fma_f32 v[46:47], v[52:53], v[52:53], v[46:47]
	v_pk_fma_f32 v[48:49], v[60:61], v[60:61], v[48:49]
	v_add_f32_e32 v46, v46, v47
	v_add_f32_e32 v46, v46, v48
	v_add_f32_e32 v46, v46, v49
	ds_bpermute_b32 v47, v39, v46
	s_waitcnt lgkmcnt(0)
	v_add_f32_e32 v46, v46, v47
	ds_bpermute_b32 v47, v40, v46
	s_waitcnt lgkmcnt(0)
	v_add_f32_e32 v46, v46, v47
	ds_bpermute_b32 v47, v41, v46
	s_waitcnt lgkmcnt(0)
	v_add_f32_e32 v46, v46, v47
	ds_bpermute_b32 v47, v42, v46
	s_waitcnt lgkmcnt(0)
	v_add_f32_e32 v46, v46, v47
	ds_bpermute_b32 v47, v43, v46
	s_waitcnt lgkmcnt(0)
	v_add_f32_e32 v46, v46, v47
	ds_bpermute_b32 v47, v44, v46
	s_and_saveexec_b64 s[2:3], vcc
	s_load_dwordx4 s[16:19], s[0:1], 0x210
	v_lshlrev_b64 v[48:49], 2, v[16:17]
	s_waitcnt lgkmcnt(0)
	v_lshl_add_u64 v[50:51], s[16:17], 0, v[48:49]
	v_lshl_add_u64 v[48:49], s[18:19], 0, v[48:49]
	global_store_dword v[50:51], v19, off
	global_store_dword v[48:49], v19, off
	s_branch .LBB0_1400

.LBB0_2341:
	s_cmp_gt_i32 s44, 10
	s_waitcnt lgkmcnt(0)
	s_cselect_b64 s[2:3], -1, 0
	s_cmp_lt_i32 s45, 11
	s_cselect_b64 s[4:5], -1, 0
	s_or_b64 s[2:3], s[2:3], s[4:5]
	s_and_b64 vcc, exec, s[2:3]
	s_cbranch_vccnz .LBB0_2401
	v_mbcnt_hi_u32_b32 v38, -1, v210
	v_mov_b32_e32 v0, v38
	v_mov_b32_e32 v1, v38
	s_mov_b32 s2, 0x8000
	v_add_u32_e32 v1, s70, v1
	v_ashrrev_i32_e32 v1, 6, v1
	v_lshl_add_u32 v16, s22, 3, v1
	v_cmp_gt_i32_e32 vcc, s2, v16
	s_and_saveexec_b64 s[4:5], vcc
	s_cbranch_execz .LBB0_2347
	s_load_dwordx2 s[6:7], s[0:1], 0x140
	s_load_dwordx2 s[8:9], s[0:1], 0x158
	s_load_dwordx2 s[2:3], s[0:1], 0x18
	s_load_dwordx2 s[10:11], s[0:1], 0xb8
	v_and_b32_e32 v1, 63, v0
	v_and_b32_e32 v0, 64, v38
	v_add_u32_e32 v2, 64, v0
	s_waitcnt lgkmcnt(0)
	s_add_u32 s14, s2, 0x2000
	v_xor_b32_e32 v3, 32, v38
	s_addc_u32 s15, s3, 0
	v_cmp_lt_i32_e64 s[2:3], v3, v2
	v_lshlrev_b32_e32 v0, 2, v1
	v_mov_b32_e32 v19, 0
	v_cndmask_b32_e64 v3, v38, v3, s[2:3]
	v_lshlrev_b32_e32 v39, 2, v3
	v_xor_b32_e32 v3, 16, v38
	v_cmp_lt_i32_e64 s[2:3], v3, v2
	v_mov_b32_e32 v5, v19
	v_mov_b32_e32 v7, v19
	v_cndmask_b32_e64 v3, v38, v3, s[2:3]
	v_lshlrev_b32_e32 v40, 2, v3
	v_xor_b32_e32 v3, 8, v38
	v_cmp_lt_i32_e64 s[2:3], v3, v2
	v_lshlrev_b32_e32 v18, 4, v1
	v_lshl_add_u64 v[20:21], s[14:15], 0, v[18:19]
	v_cndmask_b32_e64 v3, v38, v3, s[2:3]
	v_lshlrev_b32_e32 v41, 2, v3
	v_xor_b32_e32 v3, 4, v38
	v_cmp_lt_i32_e64 s[2:3], v3, v2
	v_mov_b32_e32 v9, v19
	v_lshl_add_u64 v[28:29], s[10:11], 0, v[18:19]
	v_cndmask_b32_e64 v3, v38, v3, s[2:3]
	v_lshlrev_b32_e32 v42, 2, v3
	v_xor_b32_e32 v3, 2, v38
	v_cmp_lt_i32_e64 s[2:3], v3, v2
	v_lshlrev_b32_e32 v18, 3, v1
	v_cmp_eq_u32_e32 vcc, 0, v1
	v_cndmask_b32_e64 v3, v38, v3, s[2:3]
	v_lshlrev_b32_e32 v43, 2, v3
	v_xor_b32_e32 v3, 1, v38
	v_cmp_lt_i32_e64 s[2:3], v3, v2
	s_lshl_b32 s12, s42, 3
	v_lshl_add_u64 v[30:31], s[8:9], 0, v[18:19]
	v_cndmask_b32_e64 v2, v38, v3, s[2:3]
	v_lshlrev_b32_e32 v44, 2, v2
	v_or_b32_e32 v2, 0x100, v0
	v_lshlrev_b32_e32 v4, 2, v2
	v_lshl_add_u64 v[22:23], s[14:15], 0, v[4:5]
	v_or_b32_e32 v4, 0x200, v0
	v_lshlrev_b32_e32 v6, 2, v4
	v_lshl_add_u64 v[24:25], s[14:15], 0, v[6:7]
	v_or_b32_e32 v6, 0x300, v0
	v_lshlrev_b32_e32 v8, 2, v6
	v_lshl_add_u64 v[26:27], s[14:15], 0, v[8:9]
	s_mov_b64 s[8:9], 0
	v_mov_b32_e32 v45, 0x358637bd
	s_mov_b32 s13, 0x800000
	s_mov_b64 s[10:11], 0x1000
	v_lshlrev_b32_e32 v18, 2, v0
	v_lshlrev_b32_e32 v32, 2, v2
	v_mov_b32_e32 v33, v19
	v_lshlrev_b32_e32 v34, 2, v4
	v_mov_b32_e32 v35, v19
	v_lshlrev_b32_e32 v36, 2, v6
	v_mov_b32_e32 v37, v19
	s_movk_i32 s14, 0x7fff
	v_ashrrev_i32_e32 v17, 31, v16
	v_lshlrev_b64 v[134:135], 12, v[16:17]
	v_lshl_add_u64 v[134:135], v[28:29], 0, v[134:135]
	global_load_dwordx4 v[118:121], v[134:135], off
	global_load_dwordx4 v[122:125], v[134:135], off offset:1024
	global_load_dwordx4 v[126:129], v[134:135], off offset:2048
	global_load_dwordx4 v[130:133], v[134:135], off offset:3072
	s_waitcnt vmcnt(0)
	s_branch .LBB0_2345
.LBB0_2344:
	s_or_b64 exec, exec, s[2:3]
	s_waitcnt lgkmcnt(0)
	v_add_f32_e32 v46, v46, v47
	v_fmamk_f32 v46, v46, 0x3a800000, v45
	v_mul_f32_e32 v47, 0x4b800000, v46
	v_cmp_gt_f32_e64 s[2:3], s13, v46
	s_nop 1
	v_cndmask_b32_e64 v46, v46, v47, s[2:3]
	v_rsq_f32_e32 v68, v46
	v_lshlrev_b64 v[46:47], 10, v[16:17]
	v_lshl_add_u64 v[64:65], v[46:47], 1, v[30:31]
	v_add_u32_e32 v16, s12, v16
	v_mul_f32_e32 v17, 0x45800000, v68
	v_cndmask_b32_e64 v68, v68, v17, s[2:3]
	v_pk_mul_f32 v[12:13], v[12:13], v[68:69] op_sel_hi:[1,0]
	v_pk_mul_f32 v[14:15], v[14:15], v[68:69] op_sel_hi:[1,0]
	v_pk_mul_f32 v[8:9], v[8:9], v[68:69] op_sel_hi:[1,0]
	v_pk_mul_f32 v[10:11], v[10:11], v[68:69] op_sel_hi:[1,0]
	v_pk_mul_f32 v[4:5], v[4:5], v[68:69] op_sel_hi:[1,0]
	v_pk_mul_f32 v[6:7], v[6:7], v[68:69] op_sel_hi:[1,0]
	v_pk_mul_f32 v[0:1], v[0:1], v[68:69] op_sel_hi:[1,0]
	v_pk_mul_f32 v[2:3], v[2:3], v[68:69] op_sel_hi:[1,0]
	v_cmp_lt_i32_e64 s[2:3], s14, v16
	s_or_b64 s[8:9], s[2:3], s[8:9]
	s_waitcnt vmcnt(6)
	v_pk_mul_f32 v[12:13], v[12:13], v[70:71]
	v_pk_mul_f32 v[14:15], v[14:15], v[72:73]
	v_pk_add_f32 v[86:87], v[86:87], 1.0 op_sel_hi:[1,0]
	v_pk_add_f32 v[88:89], v[88:89], 1.0 op_sel_hi:[1,0]
	v_pk_fma_f32 v[12:13], v[12:13], v[86:87], v[102:103]
	v_pk_fma_f32 v[14:15], v[14:15], v[88:89], v[104:105]
	v_cvt_pk_bf16_f32 v12, v12, v13
	v_cvt_pk_bf16_f32 v13, v14, v15
	global_store_dwordx2 v[64:65], v[12:13], off
	v_pk_mul_f32 v[8:9], v[8:9], v[74:75]
	v_pk_mul_f32 v[10:11], v[10:11], v[76:77]
	v_pk_add_f32 v[90:91], v[90:91], 1.0 op_sel_hi:[1,0]
	v_pk_add_f32 v[92:93], v[92:93], 1.0 op_sel_hi:[1,0]
	v_pk_fma_f32 v[8:9], v[8:9], v[90:91], v[106:107]
	v_pk_fma_f32 v[10:11], v[10:11], v[92:93], v[108:109]
	v_cvt_pk_bf16_f32 v8, v8, v9
	v_cvt_pk_bf16_f32 v9, v10, v11
	global_store_dwordx2 v[64:65], v[8:9], off offset:512
	v_pk_mul_f32 v[4:5], v[4:5], v[78:79]
	v_pk_mul_f32 v[6:7], v[6:7], v[80:81]
	v_pk_add_f32 v[94:95], v[94:95], 1.0 op_sel_hi:[1,0]
	v_pk_add_f32 v[96:97], v[96:97], 1.0 op_sel_hi:[1,0]
	v_pk_fma_f32 v[4:5], v[4:5], v[94:95], v[110:111]
	v_pk_fma_f32 v[6:7], v[6:7], v[96:97], v[112:113]
	v_cvt_pk_bf16_f32 v4, v4, v5
	v_cvt_pk_bf16_f32 v5, v6, v7
	global_store_dwordx2 v[64:65], v[4:5], off offset:1024
	v_pk_mul_f32 v[0:1], v[0:1], v[82:83]
	v_pk_mul_f32 v[2:3], v[2:3], v[84:85]
	v_pk_add_f32 v[98:99], v[98:99], 1.0 op_sel_hi:[1,0]
	v_pk_add_f32 v[100:101], v[100:101], 1.0 op_sel_hi:[1,0]
	v_pk_fma_f32 v[0:1], v[0:1], v[98:99], v[114:115]
	v_pk_fma_f32 v[2:3], v[2:3], v[100:101], v[116:117]
	v_cvt_pk_bf16_f32 v0, v0, v1
	v_cvt_pk_bf16_f32 v1, v2, v3
	global_store_dwordx2 v[64:65], v[0:1], off offset:1536
	s_waitcnt vmcnt(6)
	s_andn2_b64 exec, exec, s[8:9]
	s_cbranch_execz .LBB0_2347
.LBB0_2345:
	v_mov_b32_e32 v12, v118
	v_mov_b32_e32 v13, v119
	v_mov_b32_e32 v14, v120
	v_mov_b32_e32 v15, v121
	v_mov_b32_e32 v8, v122
	v_mov_b32_e32 v9, v123
	v_mov_b32_e32 v10, v124
	v_mov_b32_e32 v11, v125
	v_mov_b32_e32 v4, v126
	v_mov_b32_e32 v5, v127
	v_mov_b32_e32 v6, v128
	v_mov_b32_e32 v7, v129
	v_mov_b32_e32 v0, v130
	v_mov_b32_e32 v1, v131
	v_mov_b32_e32 v2, v132
	v_mov_b32_e32 v3, v133
	v_ashrrev_i32_e32 v17, 31, v16
	v_ashrrev_i32_e32 v134, 12, v16
	v_add_u32_e32 v134, 16, v134
	v_mul_hi_i32_i24_e32 v135, 0x3000, v134
	v_mul_i32_i24_e32 v134, 0x3000, v134
	v_lshl_add_u64 v[136:137], s[6:7], 0, v[134:135]
	v_lshl_add_u64 v[138:139], v[136:137], 0, s[10:11]
	global_load_dwordx4 v[70:73], v[20:21], off
	global_load_dwordx4 v[74:77], v[22:23], off
	global_load_dwordx4 v[78:81], v[24:25], off
	global_load_dwordx4 v[82:85], v[26:27], off
	v_lshl_add_u64 v[140:141], v[138:139], 0, v[18:19]
	global_load_dwordx4 v[86:89], v[140:141], off
	v_lshl_add_u64 v[140:141], v[138:139], 0, v[32:33]
	global_load_dwordx4 v[90:93], v[140:141], off
	v_lshl_add_u64 v[140:141], v[138:139], 0, v[34:35]
	global_load_dwordx4 v[94:97], v[140:141], off
	v_lshl_add_u64 v[140:141], v[138:139], 0, v[36:37]
	global_load_dwordx4 v[98:101], v[140:141], off
	v_lshl_add_u64 v[142:143], v[136:137], 0, v[18:19]
	global_load_dwordx4 v[102:105], v[142:143], off
	global_load_dwordx4 v[106:109], v[142:143], off offset:1024
	global_load_dwordx4 v[110:113], v[142:143], off offset:2048
	global_load_dwordx4 v[114:117], v[142:143], off offset:3072
	v_add_u32_e32 v144, s12, v16
	v_min_i32_e32 v144, 0x7fff, v144
	v_ashrrev_i32_e32 v145, 31, v144
	v_lshlrev_b64 v[146:147], 12, v[144:145]
	v_lshl_add_u64 v[146:147], v[28:29], 0, v[146:147]
	global_load_dwordx4 v[118:121], v[146:147], off
	global_load_dwordx4 v[122:125], v[146:147], off offset:1024
	global_load_dwordx4 v[126:129], v[146:147], off offset:2048
	global_load_dwordx4 v[130:133], v[146:147], off offset:3072
	v_mov_b32_e32 v48, v13
	v_mov_b32_e32 v49, v9
	v_mov_b32_e32 v46, v12
	v_mov_b32_e32 v47, v8
	v_mov_b32_e32 v56, v5
	v_mov_b32_e32 v57, v1
	v_pk_mul_f32 v[48:49], v[48:49], v[48:49]
	v_mov_b32_e32 v50, v14
	v_mov_b32_e32 v51, v10
	v_mov_b32_e32 v54, v4
	v_mov_b32_e32 v55, v0
	v_pk_mul_f32 v[56:57], v[56:57], v[56:57]
	v_pk_fma_f32 v[46:47], v[46:47], v[46:47], v[48:49]
	v_mov_b32_e32 v52, v15
	v_mov_b32_e32 v53, v11
	v_mov_b32_e32 v58, v6
	v_mov_b32_e32 v59, v2
	v_pk_fma_f32 v[48:49], v[54:55], v[54:55], v[56:57]
	v_pk_fma_f32 v[46:47], v[50:51], v[50:51], v[46:47]
	v_mov_b32_e32 v60, v7
	v_mov_b32_e32 v61, v3
	v_pk_fma_f32 v[48:49], v[58:59], v[58:59], v[48:49]
	v_pk_fma_f32 v[46:47], v[52:53], v[52:53], v[46:47]
	v_pk_fma_f32 v[48:49], v[60:61], v[60:61], v[48:49]
	v_add_f32_e32 v46, v46, v47
	v_add_f32_e32 v46, v46, v48
	v_add_f32_e32 v46, v46, v49
	ds_bpermute_b32 v47, v39, v46
	s_waitcnt lgkmcnt(0)
	v_add_f32_e32 v46, v46, v47
	ds_bpermute_b32 v47, v40, v46
	s_waitcnt lgkmcnt(0)
	v_add_f32_e32 v46, v46, v47
	ds_bpermute_b32 v47, v41, v46
	s_waitcnt lgkmcnt(0)
	v_add_f32_e32 v46, v46, v47
	ds_bpermute_b32 v47, v42, v46
	s_waitcnt lgkmcnt(0)
	v_add_f32_e32 v46, v46, v47
	ds_bpermute_b32 v47, v43, v46
	s_waitcnt lgkmcnt(0)
	v_add_f32_e32 v46, v46, v47
	ds_bpermute_b32 v47, v44, v46
	s_and_saveexec_b64 s[2:3], vcc
	s_load_dwordx4 s[16:19], s[0:1], 0x210
	v_lshlrev_b64 v[48:49], 2, v[16:17]
	s_waitcnt lgkmcnt(0)
	v_lshl_add_u64 v[50:51], s[16:17], 0, v[48:49]
	v_lshl_add_u64 v[48:49], s[18:19], 0, v[48:49]
	global_store_dword v[50:51], v19, off
	global_store_dword v[48:49], v19, off
	s_branch .LBB0_2344

.LBB0_4600:
	s_cmp_gt_i32 s44, 17
	s_cselect_b64 s[2:3], -1, 0
	s_cmp_lt_i32 s45, 18
	s_cselect_b64 s[4:5], -1, 0
	s_or_b64 s[2:3], s[2:3], s[4:5]
	s_and_b64 vcc, exec, s[2:3]
	s_cbranch_vccnz .LBB0_4660
	v_mbcnt_hi_u32_b32 v38, -1, v210
	v_mov_b32_e32 v0, v38
	v_mov_b32_e32 v1, v38
	s_mov_b32 s2, 0x8000
	v_add_u32_e32 v1, s70, v1
	v_ashrrev_i32_e32 v1, 6, v1
	v_lshl_add_u32 v16, s22, 3, v1
	v_cmp_gt_i32_e32 vcc, s2, v16
	s_and_saveexec_b64 s[4:5], vcc
	s_cbranch_execz .LBB0_4606
	s_load_dwordx2 s[6:7], s[0:1], 0x140
	s_load_dwordx2 s[8:9], s[0:1], 0x158
	s_load_dwordx2 s[2:3], s[0:1], 0x18
	s_load_dwordx2 s[10:11], s[0:1], 0xb8
	v_and_b32_e32 v1, 63, v0
	v_and_b32_e32 v0, 64, v38
	v_add_u32_e32 v2, 64, v0
	s_waitcnt lgkmcnt(0)
	s_add_u32 s14, s2, 0x3000
	v_xor_b32_e32 v3, 32, v38
	s_addc_u32 s15, s3, 0
	v_cmp_lt_i32_e64 s[2:3], v3, v2
	v_lshlrev_b32_e32 v0, 2, v1
	v_mov_b32_e32 v19, 0
	v_cndmask_b32_e64 v3, v38, v3, s[2:3]
	v_lshlrev_b32_e32 v39, 2, v3
	v_xor_b32_e32 v3, 16, v38
	v_cmp_lt_i32_e64 s[2:3], v3, v2
	v_mov_b32_e32 v5, v19
	v_mov_b32_e32 v7, v19
	v_cndmask_b32_e64 v3, v38, v3, s[2:3]
	v_lshlrev_b32_e32 v40, 2, v3
	v_xor_b32_e32 v3, 8, v38
	v_cmp_lt_i32_e64 s[2:3], v3, v2
	v_lshlrev_b32_e32 v18, 4, v1
	v_lshl_add_u64 v[20:21], s[14:15], 0, v[18:19]
	v_cndmask_b32_e64 v3, v38, v3, s[2:3]
	v_lshlrev_b32_e32 v41, 2, v3
	v_xor_b32_e32 v3, 4, v38
	v_cmp_lt_i32_e64 s[2:3], v3, v2
	v_mov_b32_e32 v9, v19
	v_lshl_add_u64 v[28:29], s[10:11], 0, v[18:19]
	v_cndmask_b32_e64 v3, v38, v3, s[2:3]
	v_lshlrev_b32_e32 v42, 2, v3
	v_xor_b32_e32 v3, 2, v38
	v_cmp_lt_i32_e64 s[2:3], v3, v2
	v_lshlrev_b32_e32 v18, 3, v1
	v_cmp_eq_u32_e32 vcc, 0, v1
	v_cndmask_b32_e64 v3, v38, v3, s[2:3]
	v_lshlrev_b32_e32 v43, 2, v3
	v_xor_b32_e32 v3, 1, v38
	v_cmp_lt_i32_e64 s[2:3], v3, v2
	s_lshl_b32 s12, s42, 3
	v_lshl_add_u64 v[30:31], s[8:9], 0, v[18:19]
	v_cndmask_b32_e64 v2, v38, v3, s[2:3]
	v_lshlrev_b32_e32 v44, 2, v2
	v_or_b32_e32 v2, 0x100, v0
	v_lshlrev_b32_e32 v4, 2, v2
	v_lshl_add_u64 v[22:23], s[14:15], 0, v[4:5]
	v_or_b32_e32 v4, 0x200, v0
	v_lshlrev_b32_e32 v6, 2, v4
	v_lshl_add_u64 v[24:25], s[14:15], 0, v[6:7]
	v_or_b32_e32 v6, 0x300, v0
	v_lshlrev_b32_e32 v8, 2, v6
	v_lshl_add_u64 v[26:27], s[14:15], 0, v[8:9]
	s_mov_b64 s[8:9], 0
	v_mov_b32_e32 v45, 0x358637bd
	s_mov_b32 s13, 0x800000
	s_mov_b64 s[10:11], 0x1000
	v_lshlrev_b32_e32 v18, 2, v0
	v_lshlrev_b32_e32 v32, 2, v2
	v_mov_b32_e32 v33, v19
	v_lshlrev_b32_e32 v34, 2, v4
	v_mov_b32_e32 v35, v19
	v_lshlrev_b32_e32 v36, 2, v6
	v_mov_b32_e32 v37, v19
	s_movk_i32 s14, 0x7fff
	v_ashrrev_i32_e32 v17, 31, v16
	v_lshlrev_b64 v[134:135], 12, v[16:17]
	v_lshl_add_u64 v[134:135], v[28:29], 0, v[134:135]
	global_load_dwordx4 v[118:121], v[134:135], off
	global_load_dwordx4 v[122:125], v[134:135], off offset:1024
	global_load_dwordx4 v[126:129], v[134:135], off offset:2048
	global_load_dwordx4 v[130:133], v[134:135], off offset:3072
	s_waitcnt vmcnt(0)
	s_branch .LBB0_4604

.LBB0_4604:
	v_mov_b32_e32 v12, v118
	v_mov_b32_e32 v13, v119
	v_mov_b32_e32 v14, v120
	v_mov_b32_e32 v15, v121
	v_mov_b32_e32 v8, v122
	v_mov_b32_e32 v9, v123
	v_mov_b32_e32 v10, v124
	v_mov_b32_e32 v11, v125
	v_mov_b32_e32 v4, v126
	v_mov_b32_e32 v5, v127
	v_mov_b32_e32 v6, v128
	v_mov_b32_e32 v7, v129
	v_mov_b32_e32 v0, v130
	v_mov_b32_e32 v1, v131
	v_mov_b32_e32 v2, v132
	v_mov_b32_e32 v3, v133
	v_ashrrev_i32_e32 v17, 31, v16
	v_ashrrev_i32_e32 v134, 12, v16
	v_add_u32_e32 v134, 24, v134
	v_mul_hi_i32_i24_e32 v135, 0x3000, v134
	v_mul_i32_i24_e32 v134, 0x3000, v134
	v_lshl_add_u64 v[136:137], s[6:7], 0, v[134:135]
	v_lshl_add_u64 v[138:139], v[136:137], 0, s[10:11]
	global_load_dwordx4 v[70:73], v[20:21], off
	global_load_dwordx4 v[74:77], v[22:23], off
	global_load_dwordx4 v[78:81], v[24:25], off
	global_load_dwordx4 v[82:85], v[26:27], off
	v_lshl_add_u64 v[140:141], v[138:139], 0, v[18:19]
	global_load_dwordx4 v[86:89], v[140:141], off
	v_lshl_add_u64 v[140:141], v[138:139], 0, v[32:33]
	global_load_dwordx4 v[90:93], v[140:141], off
	v_lshl_add_u64 v[140:141], v[138:139], 0, v[34:35]
	global_load_dwordx4 v[94:97], v[140:141], off
	v_lshl_add_u64 v[140:141], v[138:139], 0, v[36:37]
	global_load_dwordx4 v[98:101], v[140:141], off
	v_lshl_add_u64 v[142:143], v[136:137], 0, v[18:19]
	global_load_dwordx4 v[102:105], v[142:143], off
	global_load_dwordx4 v[106:109], v[142:143], off offset:1024
	global_load_dwordx4 v[110:113], v[142:143], off offset:2048
	global_load_dwordx4 v[114:117], v[142:143], off offset:3072
	v_add_u32_e32 v144, s12, v16
	v_min_i32_e32 v144, 0x7fff, v144
	v_ashrrev_i32_e32 v145, 31, v144
	v_lshlrev_b64 v[146:147], 12, v[144:145]
	v_lshl_add_u64 v[146:147], v[28:29], 0, v[146:147]
	global_load_dwordx4 v[118:121], v[146:147], off
	global_load_dwordx4 v[122:125], v[146:147], off offset:1024
	global_load_dwordx4 v[126:129], v[146:147], off offset:2048
	global_load_dwordx4 v[130:133], v[146:147], off offset:3072
	v_mov_b32_e32 v48, v13
	v_mov_b32_e32 v49, v9
	v_mov_b32_e32 v46, v12
	v_mov_b32_e32 v47, v8
	v_mov_b32_e32 v56, v5
	v_mov_b32_e32 v57, v1
	v_pk_mul_f32 v[48:49], v[48:49], v[48:49]
	v_mov_b32_e32 v50, v14
	v_mov_b32_e32 v51, v10
	v_mov_b32_e32 v54, v4
	v_mov_b32_e32 v55, v0
	v_pk_mul_f32 v[56:57], v[56:57], v[56:57]
	v_pk_fma_f32 v[46:47], v[46:47], v[46:47], v[48:49]
	v_mov_b32_e32 v52, v15
	v_mov_b32_e32 v53, v11
	v_mov_b32_e32 v58, v6
	v_mov_b32_e32 v59, v2
	v_pk_fma_f32 v[48:49], v[54:55], v[54:55], v[56:57]
	v_pk_fma_f32 v[46:47], v[50:51], v[50:51], v[46:47]
	v_mov_b32_e32 v60, v7
	v_mov_b32_e32 v61, v3
	v_pk_fma_f32 v[48:49], v[58:59], v[58:59], v[48:49]
	v_pk_fma_f32 v[46:47], v[52:53], v[52:53], v[46:47]
	v_pk_fma_f32 v[48:49], v[60:61], v[60:61], v[48:49]
	v_add_f32_e32 v46, v46, v47
	v_add_f32_e32 v46, v46, v48
	v_add_f32_e32 v46, v46, v49
	ds_bpermute_b32 v47, v39, v46
	s_waitcnt lgkmcnt(0)
	v_add_f32_e32 v46, v46, v47
	ds_bpermute_b32 v47, v40, v46
	s_waitcnt lgkmcnt(0)
	v_add_f32_e32 v46, v46, v47
	ds_bpermute_b32 v47, v41, v46
	s_waitcnt lgkmcnt(0)
	v_add_f32_e32 v46, v46, v47
	ds_bpermute_b32 v47, v42, v46
	s_waitcnt lgkmcnt(0)
	v_add_f32_e32 v46, v46, v47
	ds_bpermute_b32 v47, v43, v46
	s_waitcnt lgkmcnt(0)
	v_add_f32_e32 v46, v46, v47
	ds_bpermute_b32 v47, v44, v46
	s_and_saveexec_b64 s[2:3], vcc
	s_load_dwordx4 s[16:19], s[0:1], 0x210
	v_lshlrev_b64 v[48:49], 2, v[16:17]
	s_waitcnt lgkmcnt(0)
	v_lshl_add_u64 v[50:51], s[16:17], 0, v[48:49]
	v_lshl_add_u64 v[48:49], s[18:19], 0, v[48:49]
	global_store_dword v[50:51], v19, off
	global_store_dword v[48:49], v19, off
	s_branch .LBB0_4603
